# SB and NSA output rows: v_permlane32_swap half-wave exchange, 4 dwordx4 stores per wave-item instead of 8 dwordx2
# baseline (speedup 1.0000x reference)
; DI unsigned pack2(float a, float b) { f32x2 v = {a, b}; return __builtin_bit_cast(unsigned, __builtin_convertvector(v, hwbf16x2)); }
; DI void sb_item(const bf16_t* __restrict__ P, const bf16_t* __restrict__ VT, bf16_t* __restrict__ Y, int item, char* lds) {
;     ...
;   bf16_t* yp = Y + (tokbase + qpos) * DM + hd * 64 + 4 * hh;
; #pragma unroll
;   for (int dt = 0; dt < 2; ++dt)
; #pragma unroll
;     for (int j = 0; j < 4; ++j) {
;       u32x2 v; v.x = pack2(O[dt][4 * j], O[dt][4 * j + 1]); v.y = pack2(O[dt][4 * j + 2], O[dt][4 * j + 3]);
;       *(u32x2*)(yp + dt * 32 + 8 * j) = v;
;     }
.LBB0_482:
	s_or_b64 exec, exec, s[34:35]
	v_lshlrev_b64 v[2:3], 11, v[114:115]
	v_lshl_add_u64 v[2:3], s[64:65], 0, v[2:3]
	s_lshl_b32 s28, s11, 1
	v_lshl_add_u64 v[2:3], v[2:3], 0, s[28:29]
	v_lshlrev_b32_e32 v0, 1, v113
	v_lshl_add_u64 v[2:3], v[2:3], 0, v[0:1]
	v_mbcnt_lo_u32_b32 v0, -1, 0
	v_mbcnt_hi_u32_b32 v0, -1, v0
	v_and_b32_e32 v0, 32, v0
	v_lshrrev_b32_e32 v0, 2, v0
	v_mov_b32_e32 v1, 0
	v_lshl_add_u64 v[2:3], v[2:3], 0, v[0:1]
	v_cvt_pk_bf16_f32 v32, v32, v33
	v_cvt_pk_bf16_f32 v33, v34, v35
	v_cvt_pk_bf16_f32 v34, v36, v37
	v_cvt_pk_bf16_f32 v35, v38, v39
	s_nop 1
	v_permlane32_swap_b32_e32 v32, v34
	v_permlane32_swap_b32_e32 v33, v35
	global_store_dwordx4 v[2:3], v[32:35], off
	v_cvt_pk_bf16_f32 v36, v40, v41
	v_cvt_pk_bf16_f32 v37, v42, v43
	v_cvt_pk_bf16_f32 v38, v44, v45
	v_cvt_pk_bf16_f32 v39, v46, v47
	s_nop 1
	v_permlane32_swap_b32_e32 v36, v38
	v_permlane32_swap_b32_e32 v37, v39
	global_store_dwordx4 v[2:3], v[36:39], off offset:32
	v_cvt_pk_bf16_f32 v16, v16, v17
	v_cvt_pk_bf16_f32 v17, v18, v19
	v_cvt_pk_bf16_f32 v18, v20, v21
	v_cvt_pk_bf16_f32 v19, v22, v23
	s_nop 1
	v_permlane32_swap_b32_e32 v16, v18
	v_permlane32_swap_b32_e32 v17, v19
	global_store_dwordx4 v[2:3], v[16:19], off offset:64
	s_add_i32 s8, s8, s78
	s_add_i32 s7, s7, s78
	v_cvt_pk_bf16_f32 v20, v24, v25
	v_cvt_pk_bf16_f32 v21, v26, v27
	v_cvt_pk_bf16_f32 v22, v28, v29
	v_cvt_pk_bf16_f32 v23, v30, v31
	s_nop 1
	v_permlane32_swap_b32_e32 v20, v22
	v_permlane32_swap_b32_e32 v21, v23
	global_store_dwordx4 v[2:3], v[20:23], off offset:96
	s_cmpk_gt_i32 s8, 0x7ff
	s_cbranch_scc1 .LBB0_477

; DI unsigned pack2(float a, float b) { f32x2 v = {a, b}; return __builtin_bit_cast(unsigned, __builtin_convertvector(v, hwbf16x2)); }
; DI float half_sum(float x) { float a, b; half_swap(x, a, b); return a + b; }
; DI void nsa_item(const bf16_t* __restrict__ P, const bf16_t* __restrict__ KC, const bf16_t* __restrict__ VCT,
;                  const bf16_t* __restrict__ VTS, const bf16_t* __restrict__ VTW, bf16_t* __restrict__ Y, int item, char* lds) {
;     ...
;     const float lt = half_sum(l);
;     const float sc = lt > 0.f ? g2 / lt : 0.f;
; #pragma unroll
;     for (int dt = 0; dt < 2; ++dt)
; #pragma unroll
;       for (int e = 0; e < 16; ++e) O[dt][e] = stash[(dt * 16 + e) * 512] + O[dt][e] * sc;
;   }
;   bf16_t* yp = Y + (tokbase + pos) * DM + 512 + h * 64 + 4 * hh;
; #pragma unroll
;   for (int dt = 0; dt < 2; ++dt)
; #pragma unroll
;     for (int j = 0; j < 4; ++j) {
;       u32x2 v; v.x = pack2(O[dt][4 * j], O[dt][4 * j + 1]); v.y = pack2(O[dt][4 * j + 2], O[dt][4 * j + 3]);
;       *(u32x2*)(yp + dt * 32 + 8 * j) = v;
;     }
.LBB0_865:
	v_lshlrev_b32_e32 v0, 16, v147
	v_mul_f32_e32 v0, 0xbfb8aa3b, v0
	v_exp_f32_e32 v148, v0
	v_mov_b32_e32 v163, v149
	s_nop 1
	v_permlane32_swap_b32_e32 v149, v163
	v_pk_add_f32 v[2:3], v[148:149], v[162:163]
	s_add_i32 s2, s2, s78
	v_div_scale_f32 v0, s[0:1], v2, v2, 1.0
	v_rcp_f32_e32 v4, v0
	v_div_scale_f32 v5, vcc, 1.0, v2, 1.0
	v_readlane_b32 s24, v254, 51
	v_fma_f32 v6, -v0, v4, 1.0
	v_fmac_f32_e32 v4, v6, v4
	v_mul_f32_e32 v6, v5, v4
	v_fma_f32 v7, -v0, v6, v5
	v_fmac_f32_e32 v6, v7, v4
	v_fma_f32 v0, -v0, v6, v5
	v_div_fmas_f32 v0, v0, v4, v6
	v_div_fixup_f32 v0, v0, v2, 1.0
	v_div_scale_f32 v2, s[0:1], v3, v3, v0
	v_rcp_f32_e32 v6, v2
	s_cmpk_gt_i32 s2, 0x3ff
	v_readlane_b32 s25, v254, 52
	v_fma_f32 v4, -v2, v6, 1.0
	v_fmac_f32_e32 v6, v4, v6
	v_div_scale_f32 v4, vcc, v0, v3, v0
	v_mul_f32_e32 v7, v4, v6
	v_fma_f32 v5, -v2, v7, v4
	v_fmac_f32_e32 v7, v5, v6
	v_fma_f32 v2, -v2, v7, v4
	ds_read2st64_b32 v[4:5], v154 offset1:8
	v_div_fmas_f32 v2, v2, v6, v7
	v_div_fixup_f32 v0, v2, v3, v0
	v_cmp_lt_f32_e32 vcc, 0, v3
	s_nop 1
	v_cndmask_b32_e32 v0, 0, v0, vcc
	s_waitcnt lgkmcnt(0)
	v_pk_fma_f32 v[2:3], v[32:33], v[0:1], v[4:5] op_sel_hi:[1,0,1]
	ds_read2st64_b32 v[4:5], v154 offset0:16 offset1:24
	ds_read2st64_b32 v[6:7], v154 offset0:32 offset1:40
	ds_read2st64_b32 v[8:9], v154 offset0:48 offset1:56
	ds_read2st64_b32 v[10:11], v154 offset0:64 offset1:72
	ds_read2st64_b32 v[12:13], v154 offset0:80 offset1:88
	s_waitcnt lgkmcnt(4)
	v_pk_fma_f32 v[4:5], v[34:35], v[0:1], v[4:5] op_sel_hi:[1,0,1]
	s_waitcnt lgkmcnt(3)
	v_pk_fma_f32 v[6:7], v[36:37], v[0:1], v[6:7] op_sel_hi:[1,0,1]
	s_waitcnt lgkmcnt(2)
	v_pk_fma_f32 v[8:9], v[38:39], v[0:1], v[8:9] op_sel_hi:[1,0,1]
	ds_read2st64_b32 v[14:15], v154 offset0:96 offset1:104
	ds_read2st64_b32 v[32:33], v154 offset0:112 offset1:120
	ds_read2st64_b32 v[34:35], v154 offset0:128 offset1:136
	ds_read2st64_b32 v[36:37], v154 offset0:144 offset1:152
	ds_read2st64_b32 v[38:39], v154 offset0:160 offset1:168
	s_waitcnt lgkmcnt(6)
	v_pk_fma_f32 v[10:11], v[40:41], v[0:1], v[10:11] op_sel_hi:[1,0,1]
	s_waitcnt lgkmcnt(5)
	v_pk_fma_f32 v[12:13], v[42:43], v[0:1], v[12:13] op_sel_hi:[1,0,1]
	s_waitcnt lgkmcnt(2)
	v_pk_fma_f32 v[16:17], v[16:17], v[0:1], v[34:35] op_sel_hi:[1,0,1]
	s_waitcnt lgkmcnt(1)
	v_pk_fma_f32 v[18:19], v[18:19], v[0:1], v[36:37] op_sel_hi:[1,0,1]
	s_waitcnt lgkmcnt(0)
	v_pk_fma_f32 v[20:21], v[20:21], v[0:1], v[38:39] op_sel_hi:[1,0,1]
	ds_read2st64_b32 v[34:35], v154 offset0:176 offset1:184
	ds_read2st64_b32 v[36:37], v154 offset0:192 offset1:200
	ds_read2st64_b32 v[38:39], v154 offset0:208 offset1:216
	ds_read2st64_b32 v[40:41], v154 offset0:224 offset1:232
	ds_read2st64_b32 v[42:43], v154 offset0:240 offset1:248
	s_waitcnt lgkmcnt(4)
	v_pk_fma_f32 v[22:23], v[22:23], v[0:1], v[34:35] op_sel_hi:[1,0,1]
	v_lshlrev_b64 v[34:35], 11, v[144:145]
	v_pk_fma_f32 v[14:15], v[44:45], v[0:1], v[14:15] op_sel_hi:[1,0,1]
	v_pk_fma_f32 v[32:33], v[46:47], v[0:1], v[32:33] op_sel_hi:[1,0,1]
	s_waitcnt lgkmcnt(3)
	v_pk_fma_f32 v[24:25], v[24:25], v[0:1], v[36:37] op_sel_hi:[1,0,1]
	s_waitcnt lgkmcnt(2)
	v_pk_fma_f32 v[26:27], v[26:27], v[0:1], v[38:39] op_sel_hi:[1,0,1]
	s_waitcnt lgkmcnt(1)
	v_pk_fma_f32 v[28:29], v[28:29], v[0:1], v[40:41] op_sel_hi:[1,0,1]
	s_waitcnt lgkmcnt(0)
	v_pk_fma_f32 v[30:31], v[30:31], v[0:1], v[42:43] op_sel_hi:[1,0,1]
	v_lshl_add_u64 v[34:35], s[64:65], 0, v[34:35]
	v_lshlrev_b32_e32 v0, 1, v146
	v_lshl_add_u64 v[34:35], v[34:35], 0, v[0:1]
	v_lshlrev_b32_e32 v0, 1, v153
	v_lshl_add_u64 v[34:35], v[34:35], 0, v[0:1]
	v_mbcnt_lo_u32_b32 v0, -1, 0
	v_mbcnt_hi_u32_b32 v0, -1, v0
	v_and_b32_e32 v0, 32, v0
	v_lshrrev_b32_e32 v0, 2, v0
	v_mov_b32_e32 v1, 0
	v_lshl_add_u64 v[34:35], v[34:35], 0, v[0:1]
	v_cvt_pk_bf16_f32 v2, v2, v3
	v_cvt_pk_bf16_f32 v3, v4, v5
	v_cvt_pk_bf16_f32 v4, v6, v7
	v_cvt_pk_bf16_f32 v5, v8, v9
	s_nop 1
	v_permlane32_swap_b32_e32 v2, v4
	v_permlane32_swap_b32_e32 v3, v5
	global_store_dwordx4 v[34:35], v[2:5], off offset:1024
	v_cvt_pk_bf16_f32 v6, v10, v11
	v_cvt_pk_bf16_f32 v7, v12, v13
	v_cvt_pk_bf16_f32 v8, v14, v15
	v_cvt_pk_bf16_f32 v9, v32, v33
	s_nop 1
	v_permlane32_swap_b32_e32 v6, v8
	v_permlane32_swap_b32_e32 v7, v9
	global_store_dwordx4 v[34:35], v[6:9], off offset:1056
	v_cvt_pk_bf16_f32 v16, v16, v17
	v_cvt_pk_bf16_f32 v17, v18, v19
	v_cvt_pk_bf16_f32 v18, v20, v21
	v_cvt_pk_bf16_f32 v19, v22, v23
	s_nop 1
	v_permlane32_swap_b32_e32 v16, v18
	v_permlane32_swap_b32_e32 v17, v19
	global_store_dwordx4 v[34:35], v[16:19], off offset:1088
	v_cvt_pk_bf16_f32 v20, v24, v25
	v_cvt_pk_bf16_f32 v21, v26, v27
	v_cvt_pk_bf16_f32 v22, v28, v29
	v_cvt_pk_bf16_f32 v23, v30, v31
	s_nop 1
	v_permlane32_swap_b32_e32 v20, v22
	v_permlane32_swap_b32_e32 v21, v23
	global_store_dwordx4 v[34:35], v[20:23], off offset:1120
	s_cbranch_scc1 .LBB0_860
